# k10 + B-fragment LDS base precomputed per unit (v250 = base+0x10000): the four in-loop VALU address adds per iteration in proj/gate_up K-loops replaced by ds_read offset fields (same bytes; dummy s_mo
# baseline (speedup 1.0000x reference)
.LBB0_163:
	s_ashr_i32 s5, s4, 31
	s_xor_b64 s[20:21], s[10:11], -1
	s_lshl_b64 s[10:11], s[4:5], 20
	s_add_u32 s5, s92, s10
	s_addc_u32 s10, s93, s11
	s_cmp_gt_i32 s22, 0
	s_cselect_b32 s11, 0x80000, 0
	s_add_u32 s30, s5, s11
	s_addc_u32 s31, s10, 0
	s_and_b64 s[10:11], s[42:43], exec
	s_cselect_b32 s5, s31, s7
	s_cselect_b32 s47, s30, s6
	s_ashr_i32 s29, s28, 31
	s_lshl_b64 s[10:11], s[28:29], 20
	s_add_u32 s54, s88, s10
	s_addc_u32 s55, s89, s11
	s_and_b64 s[10:11], s[42:43], exec
	s_cselect_b32 s29, s55, s1
	s_cselect_b32 s68, s54, s0
	s_cmp_gt_i32 s22, -1
	s_cselect_b64 s[10:11], -1, 0
	s_and_b64 s[26:27], s[10:11], exec
	s_cselect_b32 s52, 0, 0x80000
	s_add_u32 s26, s6, 0x80
	s_addc_u32 s27, s7, 0
	v_lshl_add_u64 v[2:3], s[26:27], 0, v[218:219]
	v_lshl_add_u64 v[222:223], v[2:3], 0, s[50:51]
	v_lshl_add_u64 v[2:3], s[26:27], 0, v[220:221]
	v_lshl_add_u64 v[224:225], v[2:3], 0, s[50:51]
	v_mov_b32_e32 v2, v0
	v_mov_b32_e32 v3, v0
	s_add_u32 s69, s0, 0x100
	v_mov_b32_e32 v1, v0
	v_mov_b32_e32 v68, 0
	s_waitcnt lgkmcnt(0)
	v_mov_b64_e32 v[6:7], v[2:3]
	v_mov_b64_e32 v[10:11], v[2:3]
	v_mov_b64_e32 v[22:23], v[2:3]
	v_mov_b64_e32 v[26:27], v[2:3]
	v_mov_b64_e32 v[38:39], v[2:3]
	v_mov_b64_e32 v[42:43], v[2:3]
	v_mov_b64_e32 v[54:55], v[2:3]
	v_mov_b64_e32 v[58:59], v[2:3]
	v_mov_b64_e32 v[14:15], v[2:3]
	v_mov_b64_e32 v[18:19], v[2:3]
	v_mov_b64_e32 v[30:31], v[2:3]
	v_mov_b64_e32 v[34:35], v[2:3]
	v_mov_b64_e32 v[46:47], v[2:3]
	v_mov_b64_e32 v[50:51], v[2:3]
	v_mov_b64_e32 v[62:63], v[2:3]
	v_mov_b64_e32 v[66:67], v[2:3]
	s_addc_u32 s70, s1, 0
	s_mov_b32 s19, -2
	s_mov_b64 s[0:1], 0
	v_mov_b64_e32 v[4:5], v[0:1]
	v_mov_b64_e32 v[8:9], v[0:1]
	v_mov_b64_e32 v[20:21], v[0:1]
	v_mov_b64_e32 v[24:25], v[0:1]
	v_mov_b64_e32 v[36:37], v[0:1]
	v_mov_b64_e32 v[40:41], v[0:1]
	v_mov_b64_e32 v[52:53], v[0:1]
	v_mov_b64_e32 v[56:57], v[0:1]
	v_mov_b64_e32 v[12:13], v[0:1]
	v_mov_b64_e32 v[16:17], v[0:1]
	v_mov_b64_e32 v[28:29], v[0:1]
	v_mov_b64_e32 v[32:33], v[0:1]
	v_mov_b64_e32 v[44:45], v[0:1]
	v_mov_b64_e32 v[48:49], v[0:1]
	v_mov_b64_e32 v[60:61], v[0:1]
	v_mov_b64_e32 v[64:65], v[0:1]
	v_mov_b32_e32 v69, v68
	v_mov_b32_e32 v70, v68
	v_mov_b32_e32 v71, v68
	v_mov_b32_e32 v72, v68
	v_mov_b32_e32 v73, v68
	v_mov_b32_e32 v74, v68
	v_mov_b32_e32 v75, v68
	v_mov_b32_e32 v84, v68
	v_mov_b32_e32 v85, v68
	v_mov_b32_e32 v86, v68
	v_mov_b32_e32 v87, v68
	v_mov_b32_e32 v88, v68
	v_mov_b32_e32 v89, v68
	v_mov_b32_e32 v90, v68
	v_mov_b32_e32 v91, v68
	v_mov_b32_e32 v100, v68
	v_mov_b32_e32 v101, v68
	v_mov_b32_e32 v102, v68
	v_mov_b32_e32 v103, v68
	v_mov_b32_e32 v104, v68
	v_mov_b32_e32 v105, v68
	v_mov_b32_e32 v106, v68
	v_mov_b32_e32 v107, v68
	v_mov_b32_e32 v116, v68
	v_mov_b32_e32 v117, v68
	v_mov_b32_e32 v118, v68
	v_mov_b32_e32 v119, v68
	v_mov_b32_e32 v120, v68
	v_mov_b32_e32 v121, v68
	v_mov_b32_e32 v122, v68
	v_mov_b32_e32 v123, v68
	v_mov_b32_e32 v76, v68
	v_mov_b32_e32 v77, v68
	v_mov_b32_e32 v78, v68
	v_mov_b32_e32 v79, v68
	v_mov_b32_e32 v80, v68
	v_mov_b32_e32 v81, v68
	v_mov_b32_e32 v82, v68
	v_mov_b32_e32 v83, v68
	v_mov_b32_e32 v92, v68
	v_mov_b32_e32 v93, v68
	v_mov_b32_e32 v94, v68
	v_mov_b32_e32 v95, v68
	v_mov_b32_e32 v96, v68
	v_mov_b32_e32 v97, v68
	v_mov_b32_e32 v98, v68
	v_mov_b32_e32 v99, v68
	v_mov_b32_e32 v108, v68
	v_mov_b32_e32 v109, v68
	v_mov_b32_e32 v110, v68
	v_mov_b32_e32 v111, v68
	v_mov_b32_e32 v112, v68
	v_mov_b32_e32 v113, v68
	v_mov_b32_e32 v114, v68
	v_mov_b32_e32 v115, v68
	v_mov_b32_e32 v124, v68
	v_mov_b32_e32 v125, v68
	v_mov_b32_e32 v126, v68
	v_mov_b32_e32 v127, v68
	v_mov_b32_e32 v128, v68
	v_mov_b32_e32 v129, v68
	v_mov_b32_e32 v130, v68
	v_mov_b32_e32 v131, v68
	s_mov_b32 s25, s44
	v_add_u32_e32 v250, 0x10000, v245
	s_branch .LBB0_165
	s_nop 0
	s_nop 0
	s_nop 0
	s_nop 0
	s_nop 0
.LBB0_165:
	s_mov_b32 s98, 0x10000
	ds_read_b128 v[148:151], v250
	ds_read_b128 v[152:155], v250 offset:1024
	ds_read_b128 v[156:159], v250 offset:2048
	ds_read_b128 v[160:163], v250 offset:3072
	s_mov_b32 s98, 0x14000
	ds_read_b128 v[132:135], v250 offset:16384
	ds_read_b128 v[136:139], v250 offset:17408
	ds_read_b128 v[140:143], v250 offset:18432
	ds_read_b128 v[144:147], v250 offset:19456
	v_lshl_add_u64 v[2:3], v[224:225], 0, s[0:1]
	s_add_i32 m0, s77, 0xc000
	s_waitcnt lgkmcnt(0)
	ds_read_b128 v[176:179], v246
	ds_read_b128 v[192:195], v246 offset:1024
	ds_read_b128 v[172:175], v246 offset:2048
	ds_read_b128 v[188:191], v246 offset:3072
	ds_read_b128 v[168:171], v246 offset:4096
	ds_read_b128 v[184:187], v246 offset:5120
	ds_read_b128 v[164:167], v246 offset:6144
	ds_read_b128 v[180:183], v246 offset:7168
	global_load_lds_dwordx4 v[2:3], off
	v_lshl_add_u64 v[2:3], v[222:223], 0, s[0:1]
	s_add_i32 m0, s77, 0xe000
	s_nop 0
	global_load_lds_dwordx4 v[2:3], off
	s_waitcnt vmcnt(8)
	s_waitcnt lgkmcnt(0)
	s_barrier
	s_setprio 1
	s_waitcnt lgkmcnt(0)
	v_mfma_f32_16x16x32_bf16 v[128:131], v[148:151], v[176:179], v[128:131]
	v_mfma_f32_16x16x32_bf16 v[124:127], v[156:159], v[176:179], v[124:127]
	v_mfma_f32_16x16x32_bf16 v[112:115], v[148:151], v[172:175], v[112:115]
	v_mfma_f32_16x16x32_bf16 v[108:111], v[156:159], v[172:175], v[108:111]
	v_mfma_f32_16x16x32_bf16 v[96:99], v[148:151], v[168:171], v[96:99]
	v_mfma_f32_16x16x32_bf16 v[92:95], v[156:159], v[168:171], v[92:95]
	v_mfma_f32_16x16x32_bf16 v[80:83], v[148:151], v[164:167], v[80:83]
	v_mfma_f32_16x16x32_bf16 v[76:79], v[156:159], v[164:167], v[76:79]
	v_mfma_f32_16x16x32_bf16 v[128:131], v[152:155], v[192:195], v[128:131]
	v_mfma_f32_16x16x32_bf16 v[124:127], v[160:163], v[192:195], v[124:127]
	v_mfma_f32_16x16x32_bf16 v[112:115], v[152:155], v[188:191], v[112:115]
	v_mfma_f32_16x16x32_bf16 v[108:111], v[160:163], v[188:191], v[108:111]
	v_mfma_f32_16x16x32_bf16 v[96:99], v[152:155], v[184:187], v[96:99]
	v_mfma_f32_16x16x32_bf16 v[92:95], v[160:163], v[184:187], v[92:95]
	v_mfma_f32_16x16x32_bf16 v[80:83], v[152:155], v[180:183], v[80:83]
	v_mfma_f32_16x16x32_bf16 v[76:79], v[160:163], v[180:183], v[76:79]
	s_setprio 0
	s_setprio 1
	v_mfma_f32_16x16x32_bf16 v[120:123], v[132:135], v[176:179], v[120:123]
	v_mfma_f32_16x16x32_bf16 v[116:119], v[140:143], v[176:179], v[116:119]
	v_mfma_f32_16x16x32_bf16 v[104:107], v[132:135], v[172:175], v[104:107]
	v_mfma_f32_16x16x32_bf16 v[100:103], v[140:143], v[172:175], v[100:103]
	v_mfma_f32_16x16x32_bf16 v[88:91], v[132:135], v[168:171], v[88:91]
	v_mfma_f32_16x16x32_bf16 v[84:87], v[140:143], v[168:171], v[84:87]
	v_mfma_f32_16x16x32_bf16 v[72:75], v[132:135], v[164:167], v[72:75]
	v_mfma_f32_16x16x32_bf16 v[68:71], v[140:143], v[164:167], v[68:71]
	v_mfma_f32_16x16x32_bf16 v[120:123], v[136:139], v[192:195], v[120:123]
	v_mfma_f32_16x16x32_bf16 v[116:119], v[144:147], v[192:195], v[116:119]
	v_mfma_f32_16x16x32_bf16 v[104:107], v[136:139], v[188:191], v[104:107]
	v_mfma_f32_16x16x32_bf16 v[100:103], v[144:147], v[188:191], v[100:103]
	v_mfma_f32_16x16x32_bf16 v[88:91], v[136:139], v[184:187], v[88:91]
	v_mfma_f32_16x16x32_bf16 v[84:87], v[144:147], v[184:187], v[84:87]
	v_mfma_f32_16x16x32_bf16 v[72:75], v[136:139], v[180:183], v[72:75]
	v_mfma_f32_16x16x32_bf16 v[68:71], v[144:147], v[180:183], v[68:71]
	s_setprio 0
	s_barrier
	v_cndmask_b32_e64 v1, 0, 1, s[20:21]
	v_cmp_ne_u32_e64 s[44:45], 1, v1
	s_andn2_b64 vcc, exec, s[20:21]
	s_cbranch_vccnz .LBB0_167
	ds_read_b128 v[176:179], v246 offset:16384
	ds_read_b128 v[192:195], v246 offset:17408
	ds_read_b128 v[172:175], v246 offset:18432
	ds_read_b128 v[188:191], v246 offset:19456
	ds_read_b128 v[168:171], v246 offset:20480
	ds_read_b128 v[184:187], v246 offset:21504
	ds_read_b128 v[164:167], v246 offset:22528
	ds_read_b128 v[180:183], v246 offset:23552

.LBB0_169:
	s_barrier
	s_mov_b32 s98, 0x18000
	ds_read_b128 v[148:151], v250 offset:32768
	ds_read_b128 v[152:155], v250 offset:33792
	ds_read_b128 v[156:159], v250 offset:34816
	ds_read_b128 v[160:163], v250 offset:35840
	s_mov_b32 s98, 0x1c000
	ds_read_b128 v[132:135], v250 offset:49152
	ds_read_b128 v[136:139], v250 offset:50176
	ds_read_b128 v[140:143], v250 offset:51200
	ds_read_b128 v[144:147], v250 offset:52224
	s_and_b64 s[26:27], s[42:43], s[26:27]
	s_and_b64 s[26:27], s[26:27], exec
	s_cselect_b32 s26, s52, s50
	s_cselect_b32 s27, 0, s51
	s_add_u32 s26, s66, s26
	s_addc_u32 s27, s67, s27
	s_mov_b32 m0, s85
	v_lshl_add_u64 v[196:197], s[26:27], 0, v[208:209]
	s_waitcnt lgkmcnt(0)
	ds_read_b128 v[176:179], v246 offset:32768
	ds_read_b128 v[192:195], v246 offset:33792
	ds_read_b128 v[172:175], v246 offset:34816
	ds_read_b128 v[188:191], v246 offset:35840
	ds_read_b128 v[168:171], v246 offset:36864
	ds_read_b128 v[184:187], v246 offset:37888
	ds_read_b128 v[164:167], v246 offset:38912
	ds_read_b128 v[180:183], v246 offset:39936
	global_load_lds_dwordx4 v[196:197], off
	v_lshl_add_u64 v[196:197], s[26:27], 0, v[212:213]
	s_mov_b32 m0, s86
	s_nop 0
	global_load_lds_dwordx4 v[196:197], off
	s_waitcnt vmcnt(8)
	s_waitcnt lgkmcnt(0)
	s_barrier
	s_setprio 1
	s_waitcnt lgkmcnt(0)
	v_mfma_f32_16x16x32_bf16 v[128:131], v[148:151], v[176:179], v[128:131]
	v_mfma_f32_16x16x32_bf16 v[124:127], v[156:159], v[176:179], v[124:127]
	v_mfma_f32_16x16x32_bf16 v[112:115], v[148:151], v[172:175], v[112:115]
	v_mfma_f32_16x16x32_bf16 v[108:111], v[156:159], v[172:175], v[108:111]
	v_mfma_f32_16x16x32_bf16 v[96:99], v[148:151], v[168:171], v[96:99]
	v_mfma_f32_16x16x32_bf16 v[92:95], v[156:159], v[168:171], v[92:95]
	v_mfma_f32_16x16x32_bf16 v[80:83], v[148:151], v[164:167], v[80:83]
	v_mfma_f32_16x16x32_bf16 v[76:79], v[156:159], v[164:167], v[76:79]
	v_mfma_f32_16x16x32_bf16 v[128:131], v[152:155], v[192:195], v[128:131]
	v_mfma_f32_16x16x32_bf16 v[124:127], v[160:163], v[192:195], v[124:127]
	v_mfma_f32_16x16x32_bf16 v[112:115], v[152:155], v[188:191], v[112:115]
	v_mfma_f32_16x16x32_bf16 v[108:111], v[160:163], v[188:191], v[108:111]
	v_mfma_f32_16x16x32_bf16 v[96:99], v[152:155], v[184:187], v[96:99]
	v_mfma_f32_16x16x32_bf16 v[92:95], v[160:163], v[184:187], v[92:95]
	v_mfma_f32_16x16x32_bf16 v[80:83], v[152:155], v[180:183], v[80:83]
	v_mfma_f32_16x16x32_bf16 v[76:79], v[160:163], v[180:183], v[76:79]
	s_setprio 0
	s_setprio 1
	v_mfma_f32_16x16x32_bf16 v[120:123], v[132:135], v[176:179], v[120:123]
	v_mfma_f32_16x16x32_bf16 v[116:119], v[140:143], v[176:179], v[116:119]
	v_mfma_f32_16x16x32_bf16 v[104:107], v[132:135], v[172:175], v[104:107]
	v_mfma_f32_16x16x32_bf16 v[100:103], v[140:143], v[172:175], v[100:103]
	v_mfma_f32_16x16x32_bf16 v[88:91], v[132:135], v[168:171], v[88:91]
	v_mfma_f32_16x16x32_bf16 v[84:87], v[140:143], v[168:171], v[84:87]
	v_mfma_f32_16x16x32_bf16 v[72:75], v[132:135], v[164:167], v[72:75]
	v_mfma_f32_16x16x32_bf16 v[68:71], v[140:143], v[164:167], v[68:71]
	v_mfma_f32_16x16x32_bf16 v[120:123], v[136:139], v[192:195], v[120:123]
	v_mfma_f32_16x16x32_bf16 v[116:119], v[144:147], v[192:195], v[116:119]
	v_mfma_f32_16x16x32_bf16 v[104:107], v[136:139], v[188:191], v[104:107]
	v_mfma_f32_16x16x32_bf16 v[100:103], v[144:147], v[188:191], v[100:103]
	v_mfma_f32_16x16x32_bf16 v[88:91], v[136:139], v[184:187], v[88:91]
	v_mfma_f32_16x16x32_bf16 v[84:87], v[144:147], v[184:187], v[84:87]
	v_mfma_f32_16x16x32_bf16 v[72:75], v[136:139], v[180:183], v[72:75]
	v_mfma_f32_16x16x32_bf16 v[68:71], v[144:147], v[180:183], v[68:71]
	s_setprio 0
	s_barrier
	s_and_b64 vcc, exec, s[44:45]
	s_cbranch_vccnz .LBB0_171
	ds_read_b128 v[176:179], v246 offset:49152
	ds_read_b128 v[192:195], v246 offset:50176
	ds_read_b128 v[172:175], v246 offset:51200
	ds_read_b128 v[188:191], v246 offset:52224
	ds_read_b128 v[168:171], v246 offset:53248
	ds_read_b128 v[184:187], v246 offset:54272
	ds_read_b128 v[164:167], v246 offset:55296
	ds_read_b128 v[180:183], v246 offset:56320

.LBB0_679:
	s_xor_b64 s[14:15], s[0:1], -1
	s_and_b64 s[0:1], s[44:45], exec
	v_readlane_b32 s0, v254, 31
	s_cselect_b32 s74, s0, -1
	s_ashr_i32 s55, s54, 31
	s_lshl_b64 s[0:1], s[54:55], 20
	s_add_u32 s0, s19, s0
	s_addc_u32 s1, s23, s1
	s_cmp_gt_i32 s74, 0
	s_cselect_b32 s20, 0x80000, 0
	s_add_u32 s56, s0, s20
	s_addc_u32 s57, s1, 0
	s_and_b64 s[0:1], s[38:39], exec
	s_cselect_b32 s33, s57, s11
	s_cselect_b32 s34, s56, s10
	s_ashr_i32 s47, s46, 31
	s_lshl_b64 s[0:1], s[46:47], 20
	s_add_u32 s58, s29, s0
	s_addc_u32 s59, s30, s1
	s_and_b64 s[0:1], s[38:39], exec
	s_cselect_b32 s35, s59, s17
	s_cselect_b32 s47, s58, s16
	s_and_b64 s[0:1], s[44:45], exec
	s_cselect_b32 s52, 0, 0x80000
	s_add_u32 s0, s10, 0x80
	s_addc_u32 s1, s11, 0
	v_lshl_add_u64 v[2:3], s[0:1], 0, v[216:217]
	v_lshl_add_u64 v[220:221], v[2:3], 0, s[12:13]
	v_lshl_add_u64 v[2:3], s[0:1], 0, v[218:219]
	v_lshl_add_u64 v[222:223], v[2:3], 0, s[12:13]
	v_mov_b32_e32 v2, v0
	v_mov_b32_e32 v3, v0
	s_add_u32 s55, s16, 0x100
	v_mov_b32_e32 v1, v0
	v_mov_b32_e32 v68, 0
	v_mov_b64_e32 v[6:7], v[2:3]
	v_mov_b64_e32 v[10:11], v[2:3]
	v_mov_b64_e32 v[22:23], v[2:3]
	v_mov_b64_e32 v[26:27], v[2:3]
	v_mov_b64_e32 v[38:39], v[2:3]
	v_mov_b64_e32 v[42:43], v[2:3]
	v_mov_b64_e32 v[54:55], v[2:3]
	v_mov_b64_e32 v[58:59], v[2:3]
	v_mov_b64_e32 v[14:15], v[2:3]
	v_mov_b64_e32 v[18:19], v[2:3]
	v_mov_b64_e32 v[30:31], v[2:3]
	v_mov_b64_e32 v[34:35], v[2:3]
	v_mov_b64_e32 v[46:47], v[2:3]
	v_mov_b64_e32 v[50:51], v[2:3]
	v_mov_b64_e32 v[62:63], v[2:3]
	v_mov_b64_e32 v[66:67], v[2:3]
	s_addc_u32 s68, s17, 0
	s_mov_b32 s69, -2
	s_mov_b64 s[0:1], 0
	v_mov_b64_e32 v[4:5], v[0:1]
	v_mov_b64_e32 v[8:9], v[0:1]
	v_mov_b64_e32 v[20:21], v[0:1]
	v_mov_b64_e32 v[24:25], v[0:1]
	v_mov_b64_e32 v[36:37], v[0:1]
	v_mov_b64_e32 v[40:41], v[0:1]
	v_mov_b64_e32 v[52:53], v[0:1]
	v_mov_b64_e32 v[56:57], v[0:1]
	v_mov_b64_e32 v[12:13], v[0:1]
	v_mov_b64_e32 v[16:17], v[0:1]
	v_mov_b64_e32 v[28:29], v[0:1]
	v_mov_b64_e32 v[32:33], v[0:1]
	v_mov_b64_e32 v[44:45], v[0:1]
	v_mov_b64_e32 v[48:49], v[0:1]
	v_mov_b64_e32 v[60:61], v[0:1]
	v_mov_b64_e32 v[64:65], v[0:1]
	v_mov_b32_e32 v69, v68
	v_mov_b32_e32 v70, v68
	v_mov_b32_e32 v71, v68
	v_mov_b32_e32 v72, v68
	v_mov_b32_e32 v73, v68
	v_mov_b32_e32 v74, v68
	v_mov_b32_e32 v75, v68
	v_mov_b32_e32 v84, v68
	v_mov_b32_e32 v85, v68
	v_mov_b32_e32 v86, v68
	v_mov_b32_e32 v87, v68
	v_mov_b32_e32 v88, v68
	v_mov_b32_e32 v89, v68
	v_mov_b32_e32 v90, v68
	v_mov_b32_e32 v91, v68
	v_mov_b32_e32 v100, v68
	v_mov_b32_e32 v101, v68
	v_mov_b32_e32 v102, v68
	v_mov_b32_e32 v103, v68
	v_mov_b32_e32 v104, v68
	v_mov_b32_e32 v105, v68
	v_mov_b32_e32 v106, v68
	v_mov_b32_e32 v107, v68
	v_mov_b32_e32 v116, v68
	v_mov_b32_e32 v117, v68
	v_mov_b32_e32 v118, v68
	v_mov_b32_e32 v119, v68
	v_mov_b32_e32 v120, v68
	v_mov_b32_e32 v121, v68
	v_mov_b32_e32 v122, v68
	v_mov_b32_e32 v123, v68
	v_mov_b32_e32 v76, v68
	v_mov_b32_e32 v77, v68
	v_mov_b32_e32 v78, v68
	v_mov_b32_e32 v79, v68
	v_mov_b32_e32 v80, v68
	v_mov_b32_e32 v81, v68
	v_mov_b32_e32 v82, v68
	v_mov_b32_e32 v83, v68
	v_mov_b32_e32 v92, v68
	v_mov_b32_e32 v93, v68
	v_mov_b32_e32 v94, v68
	v_mov_b32_e32 v95, v68
	v_mov_b32_e32 v96, v68
	v_mov_b32_e32 v97, v68
	v_mov_b32_e32 v98, v68
	v_mov_b32_e32 v99, v68
	v_mov_b32_e32 v108, v68
	v_mov_b32_e32 v109, v68
	v_mov_b32_e32 v110, v68
	v_mov_b32_e32 v111, v68
	v_mov_b32_e32 v112, v68
	v_mov_b32_e32 v113, v68
	v_mov_b32_e32 v114, v68
	v_mov_b32_e32 v115, v68
	v_mov_b32_e32 v124, v68
	v_mov_b32_e32 v125, v68
	v_mov_b32_e32 v126, v68
	v_mov_b32_e32 v127, v68
	v_mov_b32_e32 v128, v68
	v_mov_b32_e32 v129, v68
	v_mov_b32_e32 v130, v68
	v_mov_b32_e32 v131, v68
	v_add_u32_e32 v250, 0x10000, v241
	s_branch .LBB0_681
	s_nop 0
	s_nop 0
	s_nop 0
	s_nop 0
	s_nop 0
.LBB0_681:
	s_mov_b32 s98, 0x10000
	ds_read_b128 v[148:151], v250
	ds_read_b128 v[152:155], v250 offset:1024
	ds_read_b128 v[156:159], v250 offset:2048
	ds_read_b128 v[160:163], v250 offset:3072
	s_mov_b32 s98, 0x14000
	ds_read_b128 v[132:135], v250 offset:16384
	ds_read_b128 v[136:139], v250 offset:17408
	ds_read_b128 v[140:143], v250 offset:18432
	ds_read_b128 v[144:147], v250 offset:19456
	v_lshl_add_u64 v[2:3], v[222:223], 0, s[0:1]
	s_add_i32 m0, s31, 0xc000
	s_waitcnt lgkmcnt(0)
	ds_read_b128 v[176:179], v242
	ds_read_b128 v[192:195], v242 offset:1024
	ds_read_b128 v[172:175], v242 offset:2048
	ds_read_b128 v[188:191], v242 offset:3072
	ds_read_b128 v[168:171], v242 offset:4096
	ds_read_b128 v[184:187], v242 offset:5120
	ds_read_b128 v[164:167], v242 offset:6144
	ds_read_b128 v[180:183], v242 offset:7168
	global_load_lds_dwordx4 v[2:3], off
	v_lshl_add_u64 v[2:3], v[220:221], 0, s[0:1]
	s_add_i32 m0, s31, 0xe000
	s_nop 0
	global_load_lds_dwordx4 v[2:3], off
	s_waitcnt vmcnt(8)
	s_waitcnt lgkmcnt(0)
	s_barrier
	s_setprio 1
	s_waitcnt lgkmcnt(0)
	v_mfma_f32_16x16x32_bf16 v[128:131], v[148:151], v[176:179], v[128:131]
	v_mfma_f32_16x16x32_bf16 v[124:127], v[156:159], v[176:179], v[124:127]
	v_mfma_f32_16x16x32_bf16 v[112:115], v[148:151], v[172:175], v[112:115]
	v_mfma_f32_16x16x32_bf16 v[108:111], v[156:159], v[172:175], v[108:111]
	v_mfma_f32_16x16x32_bf16 v[96:99], v[148:151], v[168:171], v[96:99]
	v_mfma_f32_16x16x32_bf16 v[92:95], v[156:159], v[168:171], v[92:95]
	v_mfma_f32_16x16x32_bf16 v[80:83], v[148:151], v[164:167], v[80:83]
	v_mfma_f32_16x16x32_bf16 v[76:79], v[156:159], v[164:167], v[76:79]
	v_mfma_f32_16x16x32_bf16 v[128:131], v[152:155], v[192:195], v[128:131]
	v_mfma_f32_16x16x32_bf16 v[124:127], v[160:163], v[192:195], v[124:127]
	v_mfma_f32_16x16x32_bf16 v[112:115], v[152:155], v[188:191], v[112:115]
	v_mfma_f32_16x16x32_bf16 v[108:111], v[160:163], v[188:191], v[108:111]
	v_mfma_f32_16x16x32_bf16 v[96:99], v[152:155], v[184:187], v[96:99]
	v_mfma_f32_16x16x32_bf16 v[92:95], v[160:163], v[184:187], v[92:95]
	v_mfma_f32_16x16x32_bf16 v[80:83], v[152:155], v[180:183], v[80:83]
	v_mfma_f32_16x16x32_bf16 v[76:79], v[160:163], v[180:183], v[76:79]
	s_setprio 0
	s_setprio 1
	v_mfma_f32_16x16x32_bf16 v[120:123], v[132:135], v[176:179], v[120:123]
	v_mfma_f32_16x16x32_bf16 v[116:119], v[140:143], v[176:179], v[116:119]
	v_mfma_f32_16x16x32_bf16 v[104:107], v[132:135], v[172:175], v[104:107]
	v_mfma_f32_16x16x32_bf16 v[100:103], v[140:143], v[172:175], v[100:103]
	v_mfma_f32_16x16x32_bf16 v[88:91], v[132:135], v[168:171], v[88:91]
	v_mfma_f32_16x16x32_bf16 v[84:87], v[140:143], v[168:171], v[84:87]
	v_mfma_f32_16x16x32_bf16 v[72:75], v[132:135], v[164:167], v[72:75]
	v_mfma_f32_16x16x32_bf16 v[68:71], v[140:143], v[164:167], v[68:71]
	v_mfma_f32_16x16x32_bf16 v[120:123], v[136:139], v[192:195], v[120:123]
	v_mfma_f32_16x16x32_bf16 v[116:119], v[144:147], v[192:195], v[116:119]
	v_mfma_f32_16x16x32_bf16 v[104:107], v[136:139], v[188:191], v[104:107]
	v_mfma_f32_16x16x32_bf16 v[100:103], v[144:147], v[188:191], v[100:103]
	v_mfma_f32_16x16x32_bf16 v[88:91], v[136:139], v[184:187], v[88:91]
	v_mfma_f32_16x16x32_bf16 v[84:87], v[144:147], v[184:187], v[84:87]
	v_mfma_f32_16x16x32_bf16 v[72:75], v[136:139], v[180:183], v[72:75]
	v_mfma_f32_16x16x32_bf16 v[68:71], v[144:147], v[180:183], v[68:71]
	s_setprio 0
	s_barrier
	v_cndmask_b32_e64 v1, 0, 1, s[14:15]
	v_cmp_ne_u32_e64 s[40:41], 1, v1
	s_andn2_b64 vcc, exec, s[14:15]
	s_cbranch_vccnz .LBB0_683
	ds_read_b128 v[176:179], v242 offset:16384
	ds_read_b128 v[192:195], v242 offset:17408
	ds_read_b128 v[172:175], v242 offset:18432
	ds_read_b128 v[188:191], v242 offset:19456
	ds_read_b128 v[168:171], v242 offset:20480
	ds_read_b128 v[184:187], v242 offset:21504
	ds_read_b128 v[164:167], v242 offset:22528
	ds_read_b128 v[180:183], v242 offset:23552

.LBB0_685:
	s_barrier
	s_mov_b32 s98, 0x18000
	ds_read_b128 v[148:151], v250 offset:32768
	ds_read_b128 v[152:155], v250 offset:33792
	ds_read_b128 v[156:159], v250 offset:34816
	ds_read_b128 v[160:163], v250 offset:35840
	s_mov_b32 s98, 0x1c000
	ds_read_b128 v[132:135], v250 offset:49152
	ds_read_b128 v[136:139], v250 offset:50176
	ds_read_b128 v[140:143], v250 offset:51200
	ds_read_b128 v[144:147], v250 offset:52224
	s_and_b64 s[26:27], s[38:39], s[26:27]
	s_and_b64 s[26:27], s[26:27], exec
	s_cselect_b32 s27, s52, s12
	s_cselect_b32 s26, 0, s13
	s_add_u32 s20, s20, s27
	s_addc_u32 s21, s21, s26
	s_mov_b32 m0, s51
	v_lshl_add_u64 v[196:197], s[20:21], 0, v[214:215]
	s_waitcnt lgkmcnt(0)
	ds_read_b128 v[176:179], v242 offset:32768
	ds_read_b128 v[192:195], v242 offset:33792
	ds_read_b128 v[172:175], v242 offset:34816
	ds_read_b128 v[188:191], v242 offset:35840
	ds_read_b128 v[168:171], v242 offset:36864
	ds_read_b128 v[184:187], v242 offset:37888
	ds_read_b128 v[164:167], v242 offset:38912
	ds_read_b128 v[180:183], v242 offset:39936
	global_load_lds_dwordx4 v[196:197], off
	v_lshl_add_u64 v[196:197], s[20:21], 0, v[210:211]
	s_mov_b32 m0, s60
	s_nop 0
	global_load_lds_dwordx4 v[196:197], off
	s_waitcnt vmcnt(8)
	s_waitcnt lgkmcnt(0)
	s_barrier
	s_setprio 1
	s_waitcnt lgkmcnt(0)
	v_mfma_f32_16x16x32_bf16 v[128:131], v[148:151], v[176:179], v[128:131]
	v_mfma_f32_16x16x32_bf16 v[124:127], v[156:159], v[176:179], v[124:127]
	v_mfma_f32_16x16x32_bf16 v[112:115], v[148:151], v[172:175], v[112:115]
	v_mfma_f32_16x16x32_bf16 v[108:111], v[156:159], v[172:175], v[108:111]
	v_mfma_f32_16x16x32_bf16 v[96:99], v[148:151], v[168:171], v[96:99]
	v_mfma_f32_16x16x32_bf16 v[92:95], v[156:159], v[168:171], v[92:95]
	v_mfma_f32_16x16x32_bf16 v[80:83], v[148:151], v[164:167], v[80:83]
	v_mfma_f32_16x16x32_bf16 v[76:79], v[156:159], v[164:167], v[76:79]
	v_mfma_f32_16x16x32_bf16 v[128:131], v[152:155], v[192:195], v[128:131]
	v_mfma_f32_16x16x32_bf16 v[124:127], v[160:163], v[192:195], v[124:127]
	v_mfma_f32_16x16x32_bf16 v[112:115], v[152:155], v[188:191], v[112:115]
	v_mfma_f32_16x16x32_bf16 v[108:111], v[160:163], v[188:191], v[108:111]
	v_mfma_f32_16x16x32_bf16 v[96:99], v[152:155], v[184:187], v[96:99]
	v_mfma_f32_16x16x32_bf16 v[92:95], v[160:163], v[184:187], v[92:95]
	v_mfma_f32_16x16x32_bf16 v[80:83], v[152:155], v[180:183], v[80:83]
	v_mfma_f32_16x16x32_bf16 v[76:79], v[160:163], v[180:183], v[76:79]
	s_setprio 0
	s_setprio 1
	v_mfma_f32_16x16x32_bf16 v[120:123], v[132:135], v[176:179], v[120:123]
	v_mfma_f32_16x16x32_bf16 v[116:119], v[140:143], v[176:179], v[116:119]
	v_mfma_f32_16x16x32_bf16 v[104:107], v[132:135], v[172:175], v[104:107]
	v_mfma_f32_16x16x32_bf16 v[100:103], v[140:143], v[172:175], v[100:103]
	v_mfma_f32_16x16x32_bf16 v[88:91], v[132:135], v[168:171], v[88:91]
	v_mfma_f32_16x16x32_bf16 v[84:87], v[140:143], v[168:171], v[84:87]
	v_mfma_f32_16x16x32_bf16 v[72:75], v[132:135], v[164:167], v[72:75]
	v_mfma_f32_16x16x32_bf16 v[68:71], v[140:143], v[164:167], v[68:71]
	v_mfma_f32_16x16x32_bf16 v[120:123], v[136:139], v[192:195], v[120:123]
	v_mfma_f32_16x16x32_bf16 v[116:119], v[144:147], v[192:195], v[116:119]
	v_mfma_f32_16x16x32_bf16 v[104:107], v[136:139], v[188:191], v[104:107]
	v_mfma_f32_16x16x32_bf16 v[100:103], v[144:147], v[188:191], v[100:103]
	v_mfma_f32_16x16x32_bf16 v[88:91], v[136:139], v[184:187], v[88:91]
	v_mfma_f32_16x16x32_bf16 v[84:87], v[144:147], v[184:187], v[84:87]
	v_mfma_f32_16x16x32_bf16 v[72:75], v[136:139], v[180:183], v[72:75]
	v_mfma_f32_16x16x32_bf16 v[68:71], v[144:147], v[180:183], v[68:71]
	s_setprio 0
	s_barrier
	s_and_b64 vcc, exec, s[40:41]
	s_cbranch_vccnz .LBB0_687
	ds_read_b128 v[176:179], v242 offset:49152
	ds_read_b128 v[192:195], v242 offset:50176
	ds_read_b128 v[172:175], v242 offset:51200
	ds_read_b128 v[188:191], v242 offset:52224
	ds_read_b128 v[168:171], v242 offset:53248
	ds_read_b128 v[184:187], v242 offset:54272
	ds_read_b128 v[164:167], v242 offset:55296
	ds_read_b128 v[180:183], v242 offset:56320
